# in-proj epilogue plain tiles: packed results lane-transposed by ds_bpermute so 4 neighbouring lanes store one row's 64 contiguous bytes
# speedup vs baseline: 1.0332x; 1.0077x over previous
; #define PG8_STAGE(bufoff, gbase, voff) do { _Pragma("unroll") for (int _i = 0; _i < 2; ++_i) \
;         __builtin_amdgcn_global_load_lds((const unsigned*)((const char*)(gbase) + (voff)[_i]), (LAS unsigned*)(lds + (bufoff) + ldsw + _i * 8192), 16, 0, 0); } while (0)
; #define PG8_LDA(dst, b, h) do { _Pragma("unroll") for (int m = 0; m < 4; ++m) _Pragma("unroll") for (int k = 0; k < 2; ++k) dst[m][k] = *(const LAS bf16x8*)(lds + PG8_SA(b, h) + aoff + m * 2048 + k * 1024); } while (0)
; #define PG8_WAIT_V(n) asm volatile("s_waitcnt vmcnt(" #n ")" ::: "memory")
; #define PG8_WAIT_L(n) asm volatile("s_waitcnt lgkmcnt(" #n ")" ::: "memory")
; template <class Epi, class Sched>
; __device__ __forceinline__ void gemm_phase(LAS unsigned char* lds, const Gemm g, const Sched& S, const Epi& E) {
;     ...
;         for (int t = 0; t < nt; t += 2) {
;             const bool last = (t == nt - 2);
;             const char* a1 = cA + (size_t)(t + 1) * kstep;
;             const char* a2 = last ? nA : cA + (size_t)(t + 2) * kstep; const char* b2 = last ? nB : cB + (size_t)(t + 2) * kstep;
;             const char* a3 = a2 + kstep; const char* b3 = b2 + kstep;
;             PG8_LDB(B0, 0, 0); PG8_SCHED; PG8_LDA(At, 0, 0); PG8_STAGE(PG8_SA(1, 1), a1 + hstep, voffA);
;             PG8_WAIT_L(8); PG8_BAR; PG8_WAIT_L(0); PG8_MMA(0, 0, At, B0); PG8_BAR; PG8_SCHED;
;             PG8_LDB(B1, 0, 1); PG8_STAGE(PG8_SB(0, 0), b2, voffB);
;             PG8_BAR; PG8_WAIT_L(0); PG8_MMA(0, 1, At, B1); PG8_BAR;
;             PG8_LDA(At, 0, 1); PG8_STAGE(PG8_SA(0, 0), a2, voffA);
;             PG8_BAR; PG8_WAIT_L(0); PG8_MMA(1, 0, At, B0); PG8_BAR; PG8_SCHED;
;             PG8_STAGE(PG8_SB(0, 1), b2 + hstep, voffB);
;             PG8_WAIT_V(6); PG8_BAR; PG8_MMA(1, 1, At, B1); PG8_BAR;
;             PG8_LDB(B0, 1, 0); PG8_SCHED; PG8_LDA(At, 1, 0); PG8_STAGE(PG8_SA(0, 1), a2 + hstep, voffA);
;             PG8_WAIT_L(8); PG8_BAR; PG8_WAIT_L(0); PG8_MMA(0, 0, At, B0); PG8_BAR; PG8_SCHED;
;             PG8_LDB(B1, 1, 1); PG8_STAGE(PG8_SB(1, 0), b3, voffB);
;             PG8_BAR; PG8_WAIT_L(0); PG8_MMA(0, 1, At, B1); PG8_BAR;
;             PG8_LDA(At, 1, 1); PG8_STAGE(PG8_SA(1, 0), a3, voffA);
;             PG8_BAR; PG8_WAIT_L(0); PG8_MMA(1, 0, At, B0); PG8_BAR; PG8_SCHED;
;             PG8_STAGE(PG8_SB(1, 1), b3 + hstep, voffB);
;             PG8_WAIT_V(6); PG8_BAR; PG8_MMA(1, 1, At, B1); PG8_BAR;
.LBB0_1045:
	s_add_u32 s20, s0, 0xfffc0080
	s_addc_u32 s21, s1, -1
	s_add_i32 s57, 0, 0x10000
	v_add_u32_e32 v0, s57, v147
	ds_read_b128 v[130:133], v0
	ds_read_b128 v[154:157], v0 offset:1024
	ds_read_b128 v[172:175], v0 offset:2048
	ds_read_b128 v[176:179], v0 offset:3072
	s_cmp_eq_u32 s56, 12
	s_cselect_b32 s23, s41, s21
	s_cselect_b32 s22, s52, s20
	s_cselect_b32 s21, s43, s55
	s_cselect_b32 s20, s53, s54
	v_lshl_add_u64 v[158:159], s[0:1], 0, v[150:151]
	s_add_i32 m0, s26, 0xc000
	ds_read_b128 v[180:183], v160
	ds_read_b128 v[184:187], v160 offset:1024
	ds_read_b128 v[188:191], v160 offset:2048
	ds_read_b128 v[192:195], v160 offset:3072
	ds_read_b128 v[212:215], v160 offset:4096
	ds_read_b128 v[216:219], v160 offset:5120
	ds_read_b128 v[220:223], v160 offset:6144
	ds_read_b128 v[224:227], v160 offset:7168
	global_load_lds_dwordx4 v[158:159], off
	v_lshl_add_u64 v[158:159], s[0:1], 0, v[152:153]
	s_add_i32 m0, s26, 0xe000
	s_nop 0
	global_load_lds_dwordx4 v[158:159], off
	s_waitcnt lgkmcnt(8)
	s_barrier
	s_waitcnt lgkmcnt(0)
	s_setprio 1
	s_waitcnt lgkmcnt(0)
	v_mfma_f32_16x16x32_bf16 v[126:129], v[130:133], v[180:183], v[126:129]
	v_mfma_f32_16x16x32_bf16 v[122:125], v[172:175], v[180:183], v[122:125]
	v_mfma_f32_16x16x32_bf16 v[114:117], v[130:133], v[188:191], v[114:117]
	v_mfma_f32_16x16x32_bf16 v[106:109], v[172:175], v[188:191], v[106:109]
	v_mfma_f32_16x16x32_bf16 v[102:105], v[130:133], v[212:215], v[102:105]
	v_mfma_f32_16x16x32_bf16 v[94:97], v[172:175], v[212:215], v[94:97]
	v_mfma_f32_16x16x32_bf16 v[86:89], v[130:133], v[220:223], v[86:89]
	v_mfma_f32_16x16x32_bf16 v[78:81], v[172:175], v[220:223], v[78:81]
	v_mfma_f32_16x16x32_bf16 v[126:129], v[154:157], v[184:187], v[126:129]
	v_mfma_f32_16x16x32_bf16 v[122:125], v[176:179], v[184:187], v[122:125]
	v_mfma_f32_16x16x32_bf16 v[114:117], v[154:157], v[192:195], v[114:117]
	v_mfma_f32_16x16x32_bf16 v[106:109], v[176:179], v[192:195], v[106:109]
	v_mfma_f32_16x16x32_bf16 v[102:105], v[154:157], v[216:219], v[102:105]
	v_mfma_f32_16x16x32_bf16 v[94:97], v[176:179], v[216:219], v[94:97]
	v_mfma_f32_16x16x32_bf16 v[86:89], v[154:157], v[224:227], v[86:89]
	v_mfma_f32_16x16x32_bf16 v[78:81], v[176:179], v[224:227], v[78:81]
	s_setprio 0
	s_barrier
	s_add_i32 s60, 0, 0x14000
	s_add_i32 s57, s57, s25
	v_add_u32_e32 v0, s60, v147
	v_lshl_add_u64 v[158:159], s[20:21], 0, v[138:139]
	s_mov_b32 m0, s57
	ds_read_b128 v[228:231], v0
	ds_read_b128 v[232:235], v0 offset:1024
	ds_read_b128 v[236:239], v0 offset:2048
	ds_read_b128 v[240:243], v0 offset:3072
	global_load_lds_dwordx4 v[158:159], off
	v_lshl_add_u64 v[196:197], s[20:21], 0, v[134:135]
	s_add_i32 m0, s57, 0x2000
	s_nop 0
	global_load_lds_dwordx4 v[196:197], off
	s_barrier
	s_waitcnt lgkmcnt(0)
	s_setprio 1
	s_waitcnt lgkmcnt(0)
	v_mfma_f32_16x16x32_bf16 v[118:121], v[228:231], v[180:183], v[118:121]
	v_mfma_f32_16x16x32_bf16 v[110:113], v[236:239], v[180:183], v[110:113]
	v_mfma_f32_16x16x32_bf16 v[98:101], v[228:231], v[188:191], v[98:101]
	v_mfma_f32_16x16x32_bf16 v[90:93], v[236:239], v[188:191], v[90:93]
	v_mfma_f32_16x16x32_bf16 v[82:85], v[228:231], v[212:215], v[82:85]
	v_mfma_f32_16x16x32_bf16 v[74:77], v[236:239], v[212:215], v[74:77]
	v_mfma_f32_16x16x32_bf16 v[70:73], v[228:231], v[220:223], v[70:73]
	v_mfma_f32_16x16x32_bf16 v[66:69], v[236:239], v[220:223], v[66:69]
	v_mfma_f32_16x16x32_bf16 v[118:121], v[232:235], v[184:187], v[118:121]
	v_mfma_f32_16x16x32_bf16 v[110:113], v[240:243], v[184:187], v[110:113]
	v_mfma_f32_16x16x32_bf16 v[98:101], v[232:235], v[192:195], v[98:101]
	v_mfma_f32_16x16x32_bf16 v[90:93], v[240:243], v[192:195], v[90:93]
	v_mfma_f32_16x16x32_bf16 v[82:85], v[232:235], v[216:219], v[82:85]
	v_mfma_f32_16x16x32_bf16 v[74:77], v[240:243], v[216:219], v[74:77]
	v_mfma_f32_16x16x32_bf16 v[70:73], v[232:235], v[224:227], v[70:73]
	v_mfma_f32_16x16x32_bf16 v[66:69], v[240:243], v[224:227], v[66:69]
	s_setprio 0
	s_mov_b32 m0, s26
	v_lshl_add_u64 v[244:245], s[22:23], 0, v[140:141]
	s_barrier
	ds_read_b128 v[180:183], v160 offset:16384
	ds_read_b128 v[184:187], v160 offset:17408
	ds_read_b128 v[188:191], v160 offset:18432
	ds_read_b128 v[192:195], v160 offset:19456
	ds_read_b128 v[212:215], v160 offset:20480
	ds_read_b128 v[216:219], v160 offset:21504
	ds_read_b128 v[220:223], v160 offset:22528
	ds_read_b128 v[224:227], v160 offset:23552
	global_load_lds_dwordx4 v[244:245], off
	v_lshl_add_u64 v[246:247], s[22:23], 0, v[136:137]
	s_mov_b32 m0, s27
	s_nop 0
	global_load_lds_dwordx4 v[246:247], off
	s_barrier
	s_waitcnt lgkmcnt(0)
	s_setprio 1
	s_waitcnt lgkmcnt(0)
	v_mfma_f32_16x16x32_bf16 v[62:65], v[130:133], v[180:183], v[62:65]
	v_mfma_f32_16x16x32_bf16 v[58:61], v[172:175], v[180:183], v[58:61]
	v_mfma_f32_16x16x32_bf16 v[50:53], v[130:133], v[188:191], v[50:53]
	v_mfma_f32_16x16x32_bf16 v[42:45], v[172:175], v[188:191], v[42:45]
	v_mfma_f32_16x16x32_bf16 v[38:41], v[130:133], v[212:215], v[38:41]
	v_mfma_f32_16x16x32_bf16 v[30:33], v[172:175], v[212:215], v[30:33]
	v_mfma_f32_16x16x32_bf16 v[22:25], v[130:133], v[220:223], v[22:25]
	v_mfma_f32_16x16x32_bf16 v[14:17], v[172:175], v[220:223], v[14:17]
	v_mfma_f32_16x16x32_bf16 v[62:65], v[154:157], v[184:187], v[62:65]
	v_mfma_f32_16x16x32_bf16 v[58:61], v[176:179], v[184:187], v[58:61]
	v_mfma_f32_16x16x32_bf16 v[50:53], v[154:157], v[192:195], v[50:53]
	v_mfma_f32_16x16x32_bf16 v[42:45], v[176:179], v[192:195], v[42:45]
	v_mfma_f32_16x16x32_bf16 v[38:41], v[154:157], v[216:219], v[38:41]
	v_mfma_f32_16x16x32_bf16 v[30:33], v[176:179], v[216:219], v[30:33]
	v_mfma_f32_16x16x32_bf16 v[22:25], v[154:157], v[224:227], v[22:25]
	v_mfma_f32_16x16x32_bf16 v[14:17], v[176:179], v[224:227], v[14:17]
	s_setprio 0
	s_barrier
; #define PG8_STAGE(bufoff, gbase, voff) do { _Pragma("unroll") for (int _i = 0; _i < 2; ++_i) \
;         __builtin_amdgcn_global_load_lds((const unsigned*)((const char*)(gbase) + (voff)[_i]), (LAS unsigned*)(lds + (bufoff) + ldsw + _i * 8192), 16, 0, 0); } while (0)
; #define PG8_LDA(dst, b, h) do { _Pragma("unroll") for (int m = 0; m < 4; ++m) _Pragma("unroll") for (int k = 0; k < 2; ++k) dst[m][k] = *(const LAS bf16x8*)(lds + PG8_SA(b, h) + aoff + m * 2048 + k * 1024); } while (0)
; #define PG8_WAIT_V(n) asm volatile("s_waitcnt vmcnt(" #n ")" ::: "memory")
; #define PG8_WAIT_L(n) asm volatile("s_waitcnt lgkmcnt(" #n ")" ::: "memory")
; template <class Epi, class Sched>
; __device__ __forceinline__ void gemm_phase(LAS unsigned char* lds, const Gemm g, const Sched& S, const Epi& E) {
;     ...
;         for (int t = 0; t < nt; t += 2) {
;             const bool last = (t == nt - 2);
;             const char* a1 = cA + (size_t)(t + 1) * kstep;
;             const char* a2 = last ? nA : cA + (size_t)(t + 2) * kstep; const char* b2 = last ? nB : cB + (size_t)(t + 2) * kstep;
;             const char* a3 = a2 + kstep; const char* b3 = b2 + kstep;
;             PG8_LDB(B0, 0, 0); PG8_SCHED; PG8_LDA(At, 0, 0); PG8_STAGE(PG8_SA(1, 1), a1 + hstep, voffA);
;             PG8_WAIT_L(8); PG8_BAR; PG8_WAIT_L(0); PG8_MMA(0, 0, At, B0); PG8_BAR; PG8_SCHED;
;             PG8_LDB(B1, 0, 1); PG8_STAGE(PG8_SB(0, 0), b2, voffB);
;             PG8_BAR; PG8_WAIT_L(0); PG8_MMA(0, 1, At, B1); PG8_BAR;
;             PG8_LDA(At, 0, 1); PG8_STAGE(PG8_SA(0, 0), a2, voffA);
;             PG8_BAR; PG8_WAIT_L(0); PG8_MMA(1, 0, At, B0); PG8_BAR; PG8_SCHED;
;             PG8_STAGE(PG8_SB(0, 1), b2 + hstep, voffB);
;             PG8_WAIT_V(6); PG8_BAR; PG8_MMA(1, 1, At, B1); PG8_BAR;
;             PG8_LDB(B0, 1, 0); PG8_SCHED; PG8_LDA(At, 1, 0); PG8_STAGE(PG8_SA(0, 1), a2 + hstep, voffA);
;             PG8_WAIT_L(8); PG8_BAR; PG8_WAIT_L(0); PG8_MMA(0, 0, At, B0); PG8_BAR; PG8_SCHED;
;             PG8_LDB(B1, 1, 1); PG8_STAGE(PG8_SB(1, 0), b3, voffB);
;             PG8_BAR; PG8_WAIT_L(0); PG8_MMA(0, 1, At, B1); PG8_BAR;
;             PG8_LDA(At, 1, 1); PG8_STAGE(PG8_SA(1, 0), a3, voffA);
;             PG8_BAR; PG8_WAIT_L(0); PG8_MMA(1, 0, At, B0); PG8_BAR; PG8_SCHED;
;             PG8_STAGE(PG8_SB(1, 1), b3 + hstep, voffB);
;             PG8_WAIT_V(6); PG8_BAR; PG8_MMA(1, 1, At, B1); PG8_BAR;
	s_add_u32 s58, s20, 0x40000
	s_addc_u32 s59, s21, 0
	s_add_i32 s57, s60, s25
	v_lshl_add_u64 v[130:131], s[58:59], 0, v[138:139]
	s_mov_b32 m0, s57
	s_nop 0
	global_load_lds_dwordx4 v[130:131], off
	v_lshl_add_u64 v[130:131], s[58:59], 0, v[134:135]
	s_add_i32 m0, s57, 0x2000
	s_nop 0
	global_load_lds_dwordx4 v[130:131], off
	s_waitcnt vmcnt(6)
	s_barrier
	s_setprio 1
	v_mfma_f32_16x16x32_bf16 v[54:57], v[228:231], v[180:183], v[54:57]
	v_mfma_f32_16x16x32_bf16 v[46:49], v[236:239], v[180:183], v[46:49]
	v_mfma_f32_16x16x32_bf16 v[34:37], v[228:231], v[188:191], v[34:37]
	v_mfma_f32_16x16x32_bf16 v[26:29], v[236:239], v[188:191], v[26:29]
	v_mfma_f32_16x16x32_bf16 v[18:21], v[228:231], v[212:215], v[18:21]
	v_mfma_f32_16x16x32_bf16 v[10:13], v[236:239], v[212:215], v[10:13]
	v_mfma_f32_16x16x32_bf16 v[6:9], v[228:231], v[220:223], v[6:9]
	v_mfma_f32_16x16x32_bf16 v[2:5], v[236:239], v[220:223], v[2:5]
	v_mfma_f32_16x16x32_bf16 v[54:57], v[232:235], v[184:187], v[54:57]
	v_mfma_f32_16x16x32_bf16 v[46:49], v[240:243], v[184:187], v[46:49]
	v_mfma_f32_16x16x32_bf16 v[34:37], v[232:235], v[192:195], v[34:37]
	v_mfma_f32_16x16x32_bf16 v[26:29], v[240:243], v[192:195], v[26:29]
	v_mfma_f32_16x16x32_bf16 v[18:21], v[232:235], v[216:219], v[18:21]
	v_mfma_f32_16x16x32_bf16 v[10:13], v[240:243], v[216:219], v[10:13]
	v_mfma_f32_16x16x32_bf16 v[6:9], v[232:235], v[224:227], v[6:9]
	v_mfma_f32_16x16x32_bf16 v[2:5], v[240:243], v[224:227], v[2:5]
	s_setprio 0
	s_add_i32 s57, 0, 0x18000
	v_add_u32_e32 v0, s57, v147
	s_barrier
	ds_read_b128 v[130:133], v0
	ds_read_b128 v[154:157], v0 offset:1024
	ds_read_b128 v[172:175], v0 offset:2048
	ds_read_b128 v[176:179], v0 offset:3072
	s_add_u32 s22, s22, 0x40000
	s_addc_u32 s23, s23, 0
	s_mov_b32 m0, s28
	v_lshl_add_u64 v[228:229], s[22:23], 0, v[140:141]
	ds_read_b128 v[180:183], v160 offset:32768
	ds_read_b128 v[184:187], v160 offset:33792
	ds_read_b128 v[188:191], v160 offset:34816
	ds_read_b128 v[192:195], v160 offset:35840
	ds_read_b128 v[212:215], v160 offset:36864
	ds_read_b128 v[216:219], v160 offset:37888
	ds_read_b128 v[220:223], v160 offset:38912
	ds_read_b128 v[224:227], v160 offset:39936
	global_load_lds_dwordx4 v[228:229], off
	v_lshl_add_u64 v[228:229], s[22:23], 0, v[136:137]
	s_mov_b32 m0, s29
	s_nop 0
	global_load_lds_dwordx4 v[228:229], off
	s_waitcnt lgkmcnt(8)
	s_barrier
	s_waitcnt lgkmcnt(0)
	s_setprio 1
	s_waitcnt lgkmcnt(0)
	v_mfma_f32_16x16x32_bf16 v[126:129], v[130:133], v[180:183], v[126:129]
	v_mfma_f32_16x16x32_bf16 v[122:125], v[172:175], v[180:183], v[122:125]
	v_mfma_f32_16x16x32_bf16 v[114:117], v[130:133], v[188:191], v[114:117]
	v_mfma_f32_16x16x32_bf16 v[106:109], v[172:175], v[188:191], v[106:109]
	v_mfma_f32_16x16x32_bf16 v[102:105], v[130:133], v[212:215], v[102:105]
	v_mfma_f32_16x16x32_bf16 v[94:97], v[172:175], v[212:215], v[94:97]
	v_mfma_f32_16x16x32_bf16 v[86:89], v[130:133], v[220:223], v[86:89]
	v_mfma_f32_16x16x32_bf16 v[78:81], v[172:175], v[220:223], v[78:81]
	v_mfma_f32_16x16x32_bf16 v[126:129], v[154:157], v[184:187], v[126:129]
	v_mfma_f32_16x16x32_bf16 v[122:125], v[176:179], v[184:187], v[122:125]
	v_mfma_f32_16x16x32_bf16 v[114:117], v[154:157], v[192:195], v[114:117]
	v_mfma_f32_16x16x32_bf16 v[106:109], v[176:179], v[192:195], v[106:109]
	v_mfma_f32_16x16x32_bf16 v[102:105], v[154:157], v[216:219], v[102:105]
	v_mfma_f32_16x16x32_bf16 v[94:97], v[176:179], v[216:219], v[94:97]
	v_mfma_f32_16x16x32_bf16 v[86:89], v[154:157], v[224:227], v[86:89]
	v_mfma_f32_16x16x32_bf16 v[78:81], v[176:179], v[224:227], v[78:81]
	s_setprio 0
	s_barrier
	s_add_i32 s22, 0, 0x1c000
	s_add_i32 s23, s57, s25
	v_add_u32_e32 v0, s22, v147
	v_lshl_add_u64 v[158:159], v[158:159], 0, s[2:3]
	s_mov_b32 m0, s23
	ds_read_b128 v[228:231], v0
	ds_read_b128 v[232:235], v0 offset:1024
	ds_read_b128 v[236:239], v0 offset:2048
	ds_read_b128 v[240:243], v0 offset:3072
	global_load_lds_dwordx4 v[158:159], off
	v_lshl_add_u64 v[158:159], v[196:197], 0, s[2:3]
	s_add_i32 m0, s23, 0x2000
	s_nop 0
	global_load_lds_dwordx4 v[158:159], off
	s_barrier
	s_waitcnt lgkmcnt(0)
	s_setprio 1
	s_waitcnt lgkmcnt(0)
	v_mfma_f32_16x16x32_bf16 v[118:121], v[228:231], v[180:183], v[118:121]
	v_mfma_f32_16x16x32_bf16 v[110:113], v[236:239], v[180:183], v[110:113]
	v_mfma_f32_16x16x32_bf16 v[98:101], v[228:231], v[188:191], v[98:101]
	v_mfma_f32_16x16x32_bf16 v[90:93], v[236:239], v[188:191], v[90:93]
	v_mfma_f32_16x16x32_bf16 v[82:85], v[228:231], v[212:215], v[82:85]
	v_mfma_f32_16x16x32_bf16 v[74:77], v[236:239], v[212:215], v[74:77]
	v_mfma_f32_16x16x32_bf16 v[70:73], v[228:231], v[220:223], v[70:73]
	v_mfma_f32_16x16x32_bf16 v[66:69], v[236:239], v[220:223], v[66:69]
	v_mfma_f32_16x16x32_bf16 v[118:121], v[232:235], v[184:187], v[118:121]
	v_mfma_f32_16x16x32_bf16 v[110:113], v[240:243], v[184:187], v[110:113]
	v_mfma_f32_16x16x32_bf16 v[98:101], v[232:235], v[192:195], v[98:101]
	v_mfma_f32_16x16x32_bf16 v[90:93], v[240:243], v[192:195], v[90:93]
	v_mfma_f32_16x16x32_bf16 v[82:85], v[232:235], v[216:219], v[82:85]
	v_mfma_f32_16x16x32_bf16 v[74:77], v[240:243], v[216:219], v[74:77]
	v_mfma_f32_16x16x32_bf16 v[70:73], v[232:235], v[224:227], v[70:73]
	v_mfma_f32_16x16x32_bf16 v[66:69], v[240:243], v[224:227], v[66:69]
	s_setprio 0
	s_mov_b32 m0, s30
	v_lshl_add_u64 v[158:159], v[244:245], 0, s[2:3]
	s_barrier
	ds_read_b128 v[180:183], v160 offset:49152
	ds_read_b128 v[184:187], v160 offset:50176
	ds_read_b128 v[188:191], v160 offset:51200
	ds_read_b128 v[192:195], v160 offset:52224
	ds_read_b128 v[212:215], v160 offset:53248
	ds_read_b128 v[216:219], v160 offset:54272
	ds_read_b128 v[220:223], v160 offset:55296
	ds_read_b128 v[224:227], v160 offset:56320
	global_load_lds_dwordx4 v[158:159], off
	v_lshl_add_u64 v[158:159], v[246:247], 0, s[2:3]
	s_mov_b32 m0, s44
	s_nop 0
	global_load_lds_dwordx4 v[158:159], off
	s_barrier
; __device__ __forceinline__ unsigned cvtpk(float lo, float hi) { unsigned r; asm volatile("v_cvt_pk_bf16_f32 %0, %1, %2" : "=v"(r) : "v"(lo), "v"(hi)); return r; }
; #define PG8_STAGE(bufoff, gbase, voff) do { _Pragma("unroll") for (int _i = 0; _i < 2; ++_i) \
;         __builtin_amdgcn_global_load_lds((const unsigned*)((const char*)(gbase) + (voff)[_i]), (LAS unsigned*)(lds + (bufoff) + ldsw + _i * 8192), 16, 0, 0); } while (0)
; #define PG8_LDA(dst, b, h) do { _Pragma("unroll") for (int m = 0; m < 4; ++m) _Pragma("unroll") for (int k = 0; k < 2; ++k) dst[m][k] = *(const LAS bf16x8*)(lds + PG8_SA(b, h) + aoff + m * 2048 + k * 1024); } while (0)
; #define PG8_MMA(ai, bj, At, Bt) do { __builtin_amdgcn_s_setprio(1); _Pragma("unroll") for (int m = 0; m < 4; ++m) _Pragma("unroll") for (int n = 0; n < 2; ++n) _Pragma("unroll") for (int k = 0; k < 2; ++k) \
;         acc[ai][bj][m][n] = __builtin_amdgcn_mfma_f32_16x16x32_bf16(Bt[n][k], At[m][k], acc[ai][bj][m][n], 0, 0, 0); __builtin_amdgcn_s_setprio(0); } while (0)
; #define PG8_WAIT_V(n) asm volatile("s_waitcnt vmcnt(" #n ")" ::: "memory")
; #define PG8_WAIT_L(n) asm volatile("s_waitcnt lgkmcnt(" #n ")" ::: "memory")
; template <class Epi, class Sched>
; __device__ __forceinline__ void gemm_phase(LAS unsigned char* lds, const Gemm g, const Sched& S, const Epi& E) {
;     ...
;             PG8_BAR; PG8_WAIT_L(0); PG8_MMA(0, 1, At, B1); PG8_BAR;
;             PG8_LDA(At, 1, 1); PG8_STAGE(PG8_SA(1, 0), a3, voffA);
;             PG8_BAR; PG8_WAIT_L(0); PG8_MMA(1, 0, At, B0); PG8_BAR; PG8_SCHED;
;             PG8_STAGE(PG8_SB(1, 1), b3 + hstep, voffB);
;             PG8_WAIT_V(6); PG8_BAR; PG8_MMA(1, 1, At, B1); PG8_BAR;
;         }
;         E(acc, cur, wr, wc, fr, fq);
;     __device__ __forceinline__ void operator()(f32x4 (&acc)[2][2][4][2], const pg8::Unit& u, int wr, int wc, int fr, int fq) const {
;     ...
; #pragma unroll
;         for (int ai = 0; ai < 2; ++ai)
; #pragma unroll
;             for (int m = 0; m < 4; ++m) {
;                 u16* rowp = proj + (size_t)(row0 + ai * 128 + m * 16) * NP + col0;
; #pragma unroll
;                 for (int bj = 0; bj < 2; ++bj) {
;                     const f32x4 v0 = acc[ai][bj][m][0], v1 = acc[ai][bj][m][1];
;                     u32x4 o = {cvtpk(v0[0], v0[1]), cvtpk(v0[2], v0[3]), cvtpk(v1[0], v1[1]), cvtpk(v1[2], v1[3])};
;                     *(u32x4*)(rowp + bj * 128) = o;
	s_waitcnt lgkmcnt(0)
	s_setprio 1
	s_waitcnt lgkmcnt(0)
	v_mfma_f32_16x16x32_bf16 v[62:65], v[130:133], v[180:183], v[62:65]
	v_mfma_f32_16x16x32_bf16 v[58:61], v[172:175], v[180:183], v[58:61]
	v_mfma_f32_16x16x32_bf16 v[50:53], v[130:133], v[188:191], v[50:53]
	v_mfma_f32_16x16x32_bf16 v[42:45], v[172:175], v[188:191], v[42:45]
	v_mfma_f32_16x16x32_bf16 v[38:41], v[130:133], v[212:215], v[38:41]
	v_mfma_f32_16x16x32_bf16 v[30:33], v[172:175], v[212:215], v[30:33]
	v_mfma_f32_16x16x32_bf16 v[22:25], v[130:133], v[220:223], v[22:25]
	v_mfma_f32_16x16x32_bf16 v[14:17], v[172:175], v[220:223], v[14:17]
	v_mfma_f32_16x16x32_bf16 v[62:65], v[154:157], v[184:187], v[62:65]
	v_mfma_f32_16x16x32_bf16 v[58:61], v[176:179], v[184:187], v[58:61]
	v_mfma_f32_16x16x32_bf16 v[50:53], v[154:157], v[192:195], v[50:53]
	v_mfma_f32_16x16x32_bf16 v[42:45], v[176:179], v[192:195], v[42:45]
	v_mfma_f32_16x16x32_bf16 v[38:41], v[154:157], v[216:219], v[38:41]
	v_mfma_f32_16x16x32_bf16 v[30:33], v[176:179], v[216:219], v[30:33]
	v_mfma_f32_16x16x32_bf16 v[22:25], v[154:157], v[224:227], v[22:25]
	v_mfma_f32_16x16x32_bf16 v[14:17], v[176:179], v[224:227], v[14:17]
	s_setprio 0
	s_barrier
	s_add_u32 s20, s20, 0x40080
	s_addc_u32 s21, s21, 0
	s_add_i32 s22, s22, s25
	v_lshl_add_u64 v[130:131], s[20:21], 0, v[138:139]
	s_mov_b32 m0, s22
	s_nop 0
	global_load_lds_dwordx4 v[130:131], off
	v_lshl_add_u64 v[130:131], s[20:21], 0, v[134:135]
	s_add_i32 m0, s22, 0x2000
	s_nop 0
	global_load_lds_dwordx4 v[130:131], off
	s_waitcnt vmcnt(6)
	s_barrier
	s_setprio 1
	v_mfma_f32_16x16x32_bf16 v[54:57], v[228:231], v[180:183], v[54:57]
	v_mfma_f32_16x16x32_bf16 v[46:49], v[236:239], v[180:183], v[46:49]
	v_mfma_f32_16x16x32_bf16 v[34:37], v[228:231], v[188:191], v[34:37]
	v_mfma_f32_16x16x32_bf16 v[26:29], v[236:239], v[188:191], v[26:29]
	v_mfma_f32_16x16x32_bf16 v[18:21], v[228:231], v[212:215], v[18:21]
	v_mfma_f32_16x16x32_bf16 v[10:13], v[236:239], v[212:215], v[10:13]
	v_mfma_f32_16x16x32_bf16 v[6:9], v[228:231], v[220:223], v[6:9]
	v_mfma_f32_16x16x32_bf16 v[2:5], v[236:239], v[220:223], v[2:5]
	v_mfma_f32_16x16x32_bf16 v[54:57], v[232:235], v[184:187], v[54:57]
	v_mfma_f32_16x16x32_bf16 v[46:49], v[240:243], v[184:187], v[46:49]
	v_mfma_f32_16x16x32_bf16 v[34:37], v[232:235], v[192:195], v[34:37]
	v_mfma_f32_16x16x32_bf16 v[26:29], v[240:243], v[192:195], v[26:29]
	v_mfma_f32_16x16x32_bf16 v[18:21], v[232:235], v[216:219], v[18:21]
	v_mfma_f32_16x16x32_bf16 v[10:13], v[240:243], v[216:219], v[10:13]
	v_mfma_f32_16x16x32_bf16 v[6:9], v[232:235], v[224:227], v[6:9]
	v_mfma_f32_16x16x32_bf16 v[2:5], v[240:243], v[224:227], v[2:5]
	s_setprio 0
	s_add_i32 s56, s56, 2
	s_add_u32 s0, s0, 0x100
	s_addc_u32 s1, s1, 0
	s_add_u32 s54, s54, 0x100
	s_addc_u32 s55, s55, 0
	s_cmp_gt_u32 s56, 13
	s_barrier
	s_cbranch_scc0 .LBB0_1045
	s_lshl_b32 s23, s51, 8
	s_add_i32 s23, s23, s45
	s_lshl_b32 s22, s37, 8
	s_and_b32 s0, s37, -2
	v_or_b32_e32 v154, s23, v145
	s_cmp_lg_u32 s0, 24
	s_mov_b64 s[0:1], -1
	s_cbranch_scc0 .LBB0_1068
	s_cmp_gt_i32 s37, 27
	s_cbranch_scc1 .LBB0_1065
	s_cmp_eq_u32 s37, 9
	s_cbranch_scc1 .Lg1_plain_vt
	v_bfe_u32 v154, v198, 2, 4
	v_or_b32_e32 v154, s23, v154
	v_and_b32_e32 v156, 3, v198
	v_and_b32_e32 v157, 0xffffffe7, v142
	v_lshl_or_b32 v156, v156, 3, v157
	v_or_b32_e32 v156, s22, v156
	v_mov_b32_e32 v157, 0
	v_mov_b64_e32 v[172:173], s[14:15]
	v_mad_i64_i32 v[172:173], s[0:1], v154, s33, v[172:173]
	v_lshl_add_u64 v[172:173], v[156:157], 1, v[172:173]
	v_and_b32_e32 v158, 3, v198
	v_bfe_u32 v159, v198, 2, 4
	v_lshl_add_u32 v158, v158, 4, v159
	v_lshlrev_b32_e32 v158, 2, v158
	v_cvt_pk_bf16_f32 v216, v126, v127
	v_cvt_pk_bf16_f32 v217, v128, v129
	v_cvt_pk_bf16_f32 v218, v122, v123
	v_cvt_pk_bf16_f32 v219, v124, v125
	ds_bpermute_b32 v224, v158, v216
	ds_bpermute_b32 v225, v158, v217
	ds_bpermute_b32 v226, v158, v218
	ds_bpermute_b32 v227, v158, v219
	v_cvt_pk_bf16_f32 v220, v118, v119
	v_cvt_pk_bf16_f32 v221, v120, v121
	v_cvt_pk_bf16_f32 v222, v110, v111
	v_cvt_pk_bf16_f32 v223, v112, v113
	ds_bpermute_b32 v228, v158, v220
	ds_bpermute_b32 v229, v158, v221
	ds_bpermute_b32 v230, v158, v222
	ds_bpermute_b32 v231, v158, v223
	s_waitcnt lgkmcnt(4)
	global_store_dwordx4 v[172:173], v[224:227], off
	v_cvt_pk_bf16_f32 v216, v114, v115
	v_cvt_pk_bf16_f32 v217, v116, v117
	v_cvt_pk_bf16_f32 v218, v106, v107
	v_cvt_pk_bf16_f32 v219, v108, v109
	s_mov_b64 s[0:1], 0x58000
	v_lshl_add_u64 v[174:175], v[172:173], 0, s[0:1]
	ds_bpermute_b32 v224, v158, v216
	ds_bpermute_b32 v225, v158, v217
	ds_bpermute_b32 v226, v158, v218
	ds_bpermute_b32 v227, v158, v219
	s_waitcnt lgkmcnt(4)
	global_store_dwordx4 v[172:173], v[228:231], off offset:256
	v_cvt_pk_bf16_f32 v220, v98, v99
	v_cvt_pk_bf16_f32 v221, v100, v101
	v_cvt_pk_bf16_f32 v222, v90, v91
	v_cvt_pk_bf16_f32 v223, v92, v93
	ds_bpermute_b32 v228, v158, v220
	ds_bpermute_b32 v229, v158, v221
	ds_bpermute_b32 v230, v158, v222
	ds_bpermute_b32 v231, v158, v223
	s_waitcnt lgkmcnt(4)
	global_store_dwordx4 v[174:175], v[224:227], off
	v_cvt_pk_bf16_f32 v216, v102, v103
	v_cvt_pk_bf16_f32 v217, v104, v105
	v_cvt_pk_bf16_f32 v218, v94, v95
	v_cvt_pk_bf16_f32 v219, v96, v97
	s_mov_b64 s[0:1], 0xb0000
	v_lshl_add_u64 v[176:177], v[172:173], 0, s[0:1]
	ds_bpermute_b32 v224, v158, v216
	ds_bpermute_b32 v225, v158, v217
	ds_bpermute_b32 v226, v158, v218
	ds_bpermute_b32 v227, v158, v219
	s_waitcnt lgkmcnt(4)
	global_store_dwordx4 v[174:175], v[228:231], off offset:256
	v_cvt_pk_bf16_f32 v220, v82, v83
	v_cvt_pk_bf16_f32 v221, v84, v85
	v_cvt_pk_bf16_f32 v222, v74, v75
	v_cvt_pk_bf16_f32 v223, v76, v77
	ds_bpermute_b32 v228, v158, v220
	ds_bpermute_b32 v229, v158, v221
	ds_bpermute_b32 v230, v158, v222
	ds_bpermute_b32 v231, v158, v223
	s_waitcnt lgkmcnt(4)
; __device__ __forceinline__ unsigned cvtpk(float lo, float hi) { unsigned r; asm volatile("v_cvt_pk_bf16_f32 %0, %1, %2" : "=v"(r) : "v"(lo), "v"(hi)); return r; }
;     __device__ __forceinline__ void operator()(f32x4 (&acc)[2][2][4][2], const pg8::Unit& u, int wr, int wc, int fr, int fq) const {
;     ...
; #pragma unroll
;         for (int ai = 0; ai < 2; ++ai)
; #pragma unroll
;             for (int m = 0; m < 4; ++m) {
;                 u16* rowp = proj + (size_t)(row0 + ai * 128 + m * 16) * NP + col0;
; #pragma unroll
;                 for (int bj = 0; bj < 2; ++bj) {
;                     const f32x4 v0 = acc[ai][bj][m][0], v1 = acc[ai][bj][m][1];
;                     u32x4 o = {cvtpk(v0[0], v0[1]), cvtpk(v0[2], v0[3]), cvtpk(v1[0], v1[1]), cvtpk(v1[2], v1[3])};
;                     *(u32x4*)(rowp + bj * 128) = o;
;                     if (u.pn == 9 && bj == 1 && wc < 2) {
;                         const int r = row0 + ai * 128 + m * 16, bl = r >> 12, key = r & 4095;
;                         *(u32x4*)(kiP + (((((size_t)bl * 128 + (key >> 5)) * 4 + (cin >> 4)) * 64) + ((cin >> 3) & 1) * 32 + (key & 31)) * 8) = o;
;                     }
	global_store_dwordx4 v[176:177], v[224:227], off
	v_cvt_pk_bf16_f32 v216, v86, v87
	v_cvt_pk_bf16_f32 v217, v88, v89
	v_cvt_pk_bf16_f32 v218, v78, v79
	v_cvt_pk_bf16_f32 v219, v80, v81
	s_mov_b64 s[0:1], 0x108000
	v_lshl_add_u64 v[174:175], v[172:173], 0, s[0:1]
	ds_bpermute_b32 v224, v158, v216
	ds_bpermute_b32 v225, v158, v217
	ds_bpermute_b32 v226, v158, v218
	ds_bpermute_b32 v227, v158, v219
	s_waitcnt lgkmcnt(4)
	global_store_dwordx4 v[176:177], v[228:231], off offset:256
	v_cvt_pk_bf16_f32 v220, v70, v71
	v_cvt_pk_bf16_f32 v221, v72, v73
	v_cvt_pk_bf16_f32 v222, v66, v67
	v_cvt_pk_bf16_f32 v223, v68, v69
	ds_bpermute_b32 v228, v158, v220
	ds_bpermute_b32 v229, v158, v221
	ds_bpermute_b32 v230, v158, v222
	ds_bpermute_b32 v231, v158, v223
	s_waitcnt lgkmcnt(4)
	global_store_dwordx4 v[174:175], v[224:227], off
	v_cvt_pk_bf16_f32 v216, v62, v63
	v_cvt_pk_bf16_f32 v217, v64, v65
	v_cvt_pk_bf16_f32 v218, v58, v59
	v_cvt_pk_bf16_f32 v219, v60, v61
	s_mov_b64 s[0:1], 0x2c0000
	v_lshl_add_u64 v[176:177], v[172:173], 0, s[0:1]
	ds_bpermute_b32 v224, v158, v216
	ds_bpermute_b32 v225, v158, v217
	ds_bpermute_b32 v226, v158, v218
	ds_bpermute_b32 v227, v158, v219
	s_waitcnt lgkmcnt(4)
	global_store_dwordx4 v[174:175], v[228:231], off offset:256
	v_cvt_pk_bf16_f32 v220, v54, v55
	v_cvt_pk_bf16_f32 v221, v56, v57
	v_cvt_pk_bf16_f32 v222, v46, v47
	v_cvt_pk_bf16_f32 v223, v48, v49
	ds_bpermute_b32 v228, v158, v220
	ds_bpermute_b32 v229, v158, v221
	ds_bpermute_b32 v230, v158, v222
	ds_bpermute_b32 v231, v158, v223
	s_waitcnt lgkmcnt(4)
	global_store_dwordx4 v[176:177], v[224:227], off
	v_cvt_pk_bf16_f32 v216, v50, v51
	v_cvt_pk_bf16_f32 v217, v52, v53
	v_cvt_pk_bf16_f32 v218, v42, v43
	v_cvt_pk_bf16_f32 v219, v44, v45
	s_mov_b64 s[0:1], 0x318000
	v_lshl_add_u64 v[174:175], v[172:173], 0, s[0:1]
	ds_bpermute_b32 v224, v158, v216
	ds_bpermute_b32 v225, v158, v217
	ds_bpermute_b32 v226, v158, v218
	ds_bpermute_b32 v227, v158, v219
	s_waitcnt lgkmcnt(4)
	global_store_dwordx4 v[176:177], v[228:231], off offset:256
	v_cvt_pk_bf16_f32 v220, v34, v35
	v_cvt_pk_bf16_f32 v221, v36, v37
	v_cvt_pk_bf16_f32 v222, v26, v27
	v_cvt_pk_bf16_f32 v223, v28, v29
	ds_bpermute_b32 v228, v158, v220
	ds_bpermute_b32 v229, v158, v221
	ds_bpermute_b32 v230, v158, v222
	ds_bpermute_b32 v231, v158, v223
	s_waitcnt lgkmcnt(4)
	global_store_dwordx4 v[174:175], v[224:227], off
	v_cvt_pk_bf16_f32 v216, v38, v39
	v_cvt_pk_bf16_f32 v217, v40, v41
	v_cvt_pk_bf16_f32 v218, v30, v31
	v_cvt_pk_bf16_f32 v219, v32, v33
	s_mov_b64 s[0:1], 0x370000
	v_lshl_add_u64 v[176:177], v[172:173], 0, s[0:1]
	ds_bpermute_b32 v224, v158, v216
	ds_bpermute_b32 v225, v158, v217
	ds_bpermute_b32 v226, v158, v218
	ds_bpermute_b32 v227, v158, v219
	s_waitcnt lgkmcnt(4)
	global_store_dwordx4 v[174:175], v[228:231], off offset:256
	v_cvt_pk_bf16_f32 v220, v18, v19
	v_cvt_pk_bf16_f32 v221, v20, v21
	v_cvt_pk_bf16_f32 v222, v10, v11
	v_cvt_pk_bf16_f32 v223, v12, v13
	ds_bpermute_b32 v228, v158, v220
	ds_bpermute_b32 v229, v158, v221
	ds_bpermute_b32 v230, v158, v222
	ds_bpermute_b32 v231, v158, v223
	s_waitcnt lgkmcnt(4)
	global_store_dwordx4 v[176:177], v[224:227], off
	v_cvt_pk_bf16_f32 v216, v22, v23
	v_cvt_pk_bf16_f32 v217, v24, v25
	v_cvt_pk_bf16_f32 v218, v14, v15
	v_cvt_pk_bf16_f32 v219, v16, v17
	s_mov_b64 s[0:1], 0x3c8000
	v_lshl_add_u64 v[174:175], v[172:173], 0, s[0:1]
	ds_bpermute_b32 v224, v158, v216
	ds_bpermute_b32 v225, v158, v217
	ds_bpermute_b32 v226, v158, v218
	ds_bpermute_b32 v227, v158, v219
	s_waitcnt lgkmcnt(4)
	global_store_dwordx4 v[176:177], v[228:231], off offset:256
	v_cvt_pk_bf16_f32 v220, v6, v7
	v_cvt_pk_bf16_f32 v221, v8, v9
	v_cvt_pk_bf16_f32 v222, v2, v3
	v_cvt_pk_bf16_f32 v223, v4, v5
	ds_bpermute_b32 v228, v158, v220
	ds_bpermute_b32 v229, v158, v221
	ds_bpermute_b32 v230, v158, v222
	ds_bpermute_b32 v231, v158, v223
	s_waitcnt lgkmcnt(4)
	global_store_dwordx4 v[174:175], v[224:227], off
	s_waitcnt lgkmcnt(0)
	global_store_dwordx4 v[174:175], v[228:231], off offset:256
	s_branch .LBB0_1064
.Lg1_plain_vt:
	s_ashr_i32 s0, s23, 12
	s_ashr_i32 s1, s0, 31
	s_lshl_b64 s[0:1], s[0:1], 9
	v_mov_b64_e32 v[130:131], s[14:15]
	v_mov_b32_e32 v159, s1
	v_or_b32_e32 v0, s0, v144
	v_mad_i64_i32 v[130:131], s[0:1], v154, s33, v[130:131]
	s_cmp_eq_u32 s37, 9
	v_or_b32_e32 v156, s22, v142
	s_cselect_b64 s[0:1], -1, 0
	v_ashrrev_i32_e32 v157, 31, v156
	s_and_b64 s[20:21], s[0:1], s[34:35]
	v_lshl_add_u64 v[172:173], v[156:157], 1, v[130:131]
	v_cvt_pk_bf16_f32 v130, v126, v127
	v_cvt_pk_bf16_f32 v131, v128, v129
	v_cvt_pk_bf16_f32 v132, v122, v123
	v_cvt_pk_bf16_f32 v133, v124, v125
	s_and_b64 vcc, exec, s[20:21]
	global_store_dwordx4 v[172:173], v[130:133], off
	s_nop 1
	v_cvt_pk_bf16_f32 v130, v118, v119
	v_cvt_pk_bf16_f32 v131, v120, v121
	v_cvt_pk_bf16_f32 v132, v110, v111
	v_cvt_pk_bf16_f32 v133, v112, v113
	global_store_dwordx4 v[172:173], v[130:133], off offset:256
	s_cbranch_vccz .LBB0_1050
	s_lshr_b32 s0, s23, 3
	s_and_b32 s0, s0, 0x1f8
	v_or_b32_e32 v158, s0, v0
	v_lshlrev_b64 v[172:173], 10, v[158:159]
	v_readlane_b32 s52, v251, 1
	v_lshl_or_b32 v172, v146, 4, v172
	v_readlane_b32 s53, v251, 2
	v_readlane_b32 s54, v251, 3
	v_readlane_b32 s55, v251, 4
	v_lshl_add_u64 v[172:173], s[52:53], 0, v[172:173]
	v_readlane_b32 s56, v251, 5
	v_readlane_b32 s57, v251, 6
	v_readlane_b32 s58, v251, 7
	v_readlane_b32 s59, v251, 8
	global_store_dwordx4 v[172:173], v[130:133], off
